# P17: in GEMM steps with constant B (weights), waves 1-7 issue the first four B-tile DMA loads before the grid barrier completes; barrier join moved in front of first A-tile load
# baseline (speedup 1.0000x reference)
; __device__ __forceinline__ unsigned xb_ld(unsigned* p)              { return __hip_atomic_load(p, __ATOMIC_RELAXED, __HIP_MEMORY_SCOPE_AGENT); }
; #define XB_SPIN(cond, bar) do { unsigned _sp = 0; while (cond) { __builtin_amdgcn_s_sleep(1); \
;     if ((++_sp & 255u) == 0u) { if (xb_ld(&(bar)[XB_TMO])) break; if (_sp > XB_SPIN_CAP) { atomicAdd(&(bar)[XB_TMO], 1u); break; } } } } while (0)
; #define PG8_STAGE(bufoff, gbase, voff) do { _Pragma("unroll") for (int _i = 0; _i < 2; ++_i) { unsigned _vo = (voff)[_i]; asm volatile("" : "+v"(_vo));   \
;         __builtin_amdgcn_global_load_lds((const unsigned*)((const char*)(gbase) + _vo), (LAS unsigned*)(lds + (bufoff) + ldsw + _i * 8192), 16, 0, 0); } } while (0)
; #define PG8_WAIT_V(n) asm volatile("s_waitcnt vmcnt(" #n ")" ::: "memory")
; #define PG8_BAR __builtin_amdgcn_s_barrier()
; __device__ __forceinline__ void xcd_barrier(const XcdBarrier& b) {
;     ...
;         XB_SPIN((int)(xb_ld(&bar[XB_TOP]) - target) < 0, bar);
; __device__ __forceinline__ void gemm_phase(LAS unsigned char* lds, const Call& C, const int tid, const Args& args) {
;     ...
;     PG8_STAGE(PG8_SB(0, 0), cB, voffB); PG8_STAGE(PG8_SB(0, 1), cB + hstepB, voffB); PG8_STAGE(PG8_SA(0, 0), cA, voffA); PG8_STAGE(PG8_SA(0, 1), cA + hstepA, voffA);
;     if (wr == 1) PG8_BAR;
;     PG8_WAIT_V(2); PG8_BAR;
;     PG8_STAGE(PG8_SB(1, 0), cB + kstep, voffB); PG8_STAGE(PG8_SA(1, 0), cA + kstep, voffA); PG8_STAGE(PG8_SB(1, 1), cB + hstepB + kstep, voffB);
.Lp16a_all:
	s_waitcnt vmcnt(0) lgkmcnt(0)
	s_barrier
	s_branch .Lp16a_skip
.Lp17_others:
	v_readlane_b32 vcc_lo, v254, 15
	s_nop 3
	s_cmp_eq_u32 vcc_lo, 2
	s_cbranch_scc1 .Lp17_early
	s_cmp_lt_u32 vcc_lo, 4
	s_cbranch_scc1 .Lp16a_all
.Lp17_early:
	s_waitcnt vmcnt(0) lgkmcnt(0)
	s_mov_b32 s100, 1
.Lp16a_skip:
	s_add_i32 s20, s23, 0
	v_mov_b32_e32 v0, v242
	s_add_i32 m0, s20, 0x10000
	s_nop 0
	global_load_lds_dwordx4 v0, s[8:9]
	v_mov_b32_e32 v0, v244
	s_add_i32 m0, s20, 0x12000
	s_add_u32 s34, s8, s74
	global_load_lds_dwordx4 v0, s[8:9]
	v_mov_b32_e32 v0, v242
	s_addc_u32 s35, s9, s75
	s_add_i32 m0, s20, 0x14000
	s_nop 0
	global_load_lds_dwordx4 v0, s[34:35]
	v_mov_b32_e32 v0, v244
	s_add_i32 m0, s20, 0x16000
	s_add_u32 s0, s4, s0
	global_load_lds_dwordx4 v0, s[34:35]
	v_mov_b32_e32 v0, v205
	s_addc_u32 s1, s14, s1
	s_cmp_eq_u32 s100, 0
	s_cbranch_scc1 .Lp17_skip
	s_mov_b32 s100, 0
	s_barrier
.Lp17_skip:
	s_mov_b32 m0, s20
	s_add_i32 s72, s20, 0x2000
	global_load_lds_dwordx4 v0, s[0:1]
	v_mov_b32_e32 v0, v243
	s_mov_b32 m0, s72
	s_add_u32 s24, s0, s22
	global_load_lds_dwordx4 v0, s[0:1]
	s_addc_u32 s25, s1, 0
	s_add_i32 s73, s20, 0x4000
	v_mov_b32_e32 v0, v205
	s_mov_b32 m0, s73
	s_add_i32 s4, s20, 0x6000
	global_load_lds_dwordx4 v0, s[24:25]
	v_mov_b32_e32 v0, v243
	s_mov_b32 m0, s4
	s_cmp_eq_u32 s13, 1
	global_load_lds_dwordx4 v0, s[24:25]
	s_cselect_b64 s[24:25], -1, 0
	v_writelane_b32 v254, s24, 57
	v_mov_b32_e32 v80, v242
	s_add_i32 m0, s20, 0x18000
	v_lshl_add_u64 v[0:1], s[8:9], 0, v[80:81]
	v_lshl_add_u64 v[0:1], v[0:1], 0, s[18:19]
	v_mov_b32_e32 v80, v244
	global_load_lds_dwordx4 v[0:1], off
	s_add_i32 m0, s20, 0x1a000
	v_lshl_add_u64 v[0:1], s[8:9], 0, v[80:81]
	v_lshl_add_u64 v[0:1], v[0:1], 0, s[18:19]
	v_mov_b32_e32 v80, v205
	global_load_lds_dwordx4 v[0:1], off
	s_add_i32 s14, s20, 0x8000
	v_lshl_add_u64 v[0:1], s[0:1], 0, v[80:81]
	v_lshl_add_u64 v[0:1], v[0:1], 0, s[18:19]
	s_mov_b32 m0, s14
	v_mov_b32_e32 v80, v243
	global_load_lds_dwordx4 v[0:1], off
	s_add_i32 s52, s20, 0xa000
	v_lshl_add_u64 v[0:1], s[0:1], 0, v[80:81]
	v_lshl_add_u64 v[0:1], v[0:1], 0, s[18:19]
	s_mov_b32 m0, s52
	v_mov_b32_e32 v80, v242
	s_nop 0
	global_load_lds_dwordx4 v[0:1], off
	v_lshl_add_u64 v[0:1], s[34:35], 0, v[80:81]
	s_add_i32 m0, s20, 0x1c000
	v_lshl_add_u64 v[0:1], v[0:1], 0, s[18:19]
	s_nop 0
	global_load_lds_dwordx4 v[0:1], off
	s_cmp_lg_u32 s13, 1
	s_nop 0
	v_writelane_b32 v254, s25, 58
	s_cbranch_scc1 .LBB0_264
	s_barrier
